# phase0 modulation item: silu(cond) staging with 36 loads issued up front (was 36 serialized load-wait iterations)
# speedup vs baseline: 1.0300x; 1.0028x over previous
.LBB0_393:
	s_andn2_b64 vcc, exec, s[0:1]
	s_cbranch_vccnz .LBB0_353
	s_mov_b64 s[0:1], 0
	global_load_dword v152, v213, s[92:93]
	global_load_dword v153, v213, s[92:93] offset:1024
	global_load_dword v154, v213, s[92:93] offset:2048
	global_load_dword v155, v213, s[92:93] offset:3072
	v_mov_b32_e32 v254, v213
	global_load_dword v156, v254, s[90:91]
	global_load_dword v157, v254, s[90:91] offset:1024
	global_load_dword v158, v254, s[90:91] offset:2048
	global_load_dword v159, v254, s[90:91] offset:3072
	v_add_u32_e32 v254, 0x1000, v213
	global_load_dword v160, v254, s[90:91]
	global_load_dword v161, v254, s[90:91] offset:1024
	global_load_dword v162, v254, s[90:91] offset:2048
	global_load_dword v163, v254, s[90:91] offset:3072
	v_add_u32_e32 v254, 0x2000, v213
	global_load_dword v164, v254, s[90:91]
	global_load_dword v165, v254, s[90:91] offset:1024
	global_load_dword v166, v254, s[90:91] offset:2048
	global_load_dword v167, v254, s[90:91] offset:3072
	v_add_u32_e32 v254, 0x3000, v213
	global_load_dword v168, v254, s[90:91]
	global_load_dword v169, v254, s[90:91] offset:1024
	global_load_dword v170, v254, s[90:91] offset:2048
	global_load_dword v171, v254, s[90:91] offset:3072
	v_add_u32_e32 v254, 0x4000, v213
	global_load_dword v233, v254, s[90:91]
	global_load_dword v234, v254, s[90:91] offset:1024
	global_load_dword v235, v254, s[90:91] offset:2048
	global_load_dword v236, v254, s[90:91] offset:3072
	v_add_u32_e32 v254, 0x5000, v213
	global_load_dword v237, v254, s[90:91]
	global_load_dword v238, v254, s[90:91] offset:1024
	global_load_dword v239, v254, s[90:91] offset:2048
	global_load_dword v240, v254, s[90:91] offset:3072
	v_add_u32_e32 v254, 0x6000, v213
	global_load_dword v241, v254, s[90:91]
	global_load_dword v242, v254, s[90:91] offset:1024
	global_load_dword v243, v254, s[90:91] offset:2048
	global_load_dword v244, v254, s[90:91] offset:3072
	v_add_u32_e32 v254, 0x7000, v213
	global_load_dword v249, v254, s[90:91]
	global_load_dword v250, v254, s[90:91] offset:1024
	global_load_dword v251, v254, s[90:91] offset:2048
	global_load_dword v252, v254, s[90:91] offset:3072
	s_waitcnt vmcnt(35)
	v_mul_f32_e32 v253, 0xbfb8aa3b, v152
	v_exp_f32_e32 v253, v253
	s_nop 0
	v_add_f32_e32 v253, 1.0, v253
	v_rcp_f32_e32 v253, v253
	s_nop 0
	v_mul_f32_e32 v152, v152, v253
	ds_write_b32 v213, v152
	s_waitcnt vmcnt(34)
	v_mul_f32_e32 v253, 0xbfb8aa3b, v153
	v_exp_f32_e32 v253, v253
	s_nop 0
	v_add_f32_e32 v253, 1.0, v253
	v_rcp_f32_e32 v253, v253
	s_nop 0
	v_mul_f32_e32 v153, v153, v253
	ds_write_b32 v213, v153 offset:1024
	s_waitcnt vmcnt(33)
	v_mul_f32_e32 v253, 0xbfb8aa3b, v154
	v_exp_f32_e32 v253, v253
	s_nop 0
	v_add_f32_e32 v253, 1.0, v253
	v_rcp_f32_e32 v253, v253
	s_nop 0
	v_mul_f32_e32 v154, v154, v253
	ds_write_b32 v213, v154 offset:2048
	s_waitcnt vmcnt(32)
	v_mul_f32_e32 v253, 0xbfb8aa3b, v155
	v_exp_f32_e32 v253, v253
	s_nop 0
	v_add_f32_e32 v253, 1.0, v253
	v_rcp_f32_e32 v253, v253
	s_nop 0
	v_mul_f32_e32 v155, v155, v253
	ds_write_b32 v213, v155 offset:3072
	s_waitcnt vmcnt(31)
	v_mul_f32_e32 v253, 0xbfb8aa3b, v156
	v_exp_f32_e32 v253, v253
	s_nop 0
	v_add_f32_e32 v253, 1.0, v253
	v_rcp_f32_e32 v253, v253
	s_nop 0
	v_mul_f32_e32 v156, v156, v253
	ds_write_b32 v213, v156 offset:4096
	s_waitcnt vmcnt(30)
	v_mul_f32_e32 v253, 0xbfb8aa3b, v157
	v_exp_f32_e32 v253, v253
	s_nop 0
	v_add_f32_e32 v253, 1.0, v253
	v_rcp_f32_e32 v253, v253
	s_nop 0
	v_mul_f32_e32 v157, v157, v253
	ds_write_b32 v213, v157 offset:5120
	s_waitcnt vmcnt(29)
	v_mul_f32_e32 v253, 0xbfb8aa3b, v158
	v_exp_f32_e32 v253, v253
	s_nop 0
	v_add_f32_e32 v253, 1.0, v253
	v_rcp_f32_e32 v253, v253
	s_nop 0
	v_mul_f32_e32 v158, v158, v253
	ds_write_b32 v213, v158 offset:6144
	s_waitcnt vmcnt(28)
	v_mul_f32_e32 v253, 0xbfb8aa3b, v159
	v_exp_f32_e32 v253, v253
	s_nop 0
	v_add_f32_e32 v253, 1.0, v253
	v_rcp_f32_e32 v253, v253
	s_nop 0
	v_mul_f32_e32 v159, v159, v253
	ds_write_b32 v213, v159 offset:7168
	s_waitcnt vmcnt(27)
	v_mul_f32_e32 v253, 0xbfb8aa3b, v160
	v_exp_f32_e32 v253, v253
	s_nop 0
	v_add_f32_e32 v253, 1.0, v253
	v_rcp_f32_e32 v253, v253
	s_nop 0
	v_mul_f32_e32 v160, v160, v253
	ds_write_b32 v213, v160 offset:8192
	s_waitcnt vmcnt(26)
	v_mul_f32_e32 v253, 0xbfb8aa3b, v161
	v_exp_f32_e32 v253, v253
	s_nop 0
	v_add_f32_e32 v253, 1.0, v253
	v_rcp_f32_e32 v253, v253
	s_nop 0
	v_mul_f32_e32 v161, v161, v253
	ds_write_b32 v213, v161 offset:9216
	s_waitcnt vmcnt(25)
	v_mul_f32_e32 v253, 0xbfb8aa3b, v162
	v_exp_f32_e32 v253, v253
	s_nop 0
	v_add_f32_e32 v253, 1.0, v253
	v_rcp_f32_e32 v253, v253
	s_nop 0
	v_mul_f32_e32 v162, v162, v253
	ds_write_b32 v213, v162 offset:10240
	s_waitcnt vmcnt(24)
	v_mul_f32_e32 v253, 0xbfb8aa3b, v163
	v_exp_f32_e32 v253, v253
	s_nop 0
	v_add_f32_e32 v253, 1.0, v253
	v_rcp_f32_e32 v253, v253
	s_nop 0
	v_mul_f32_e32 v163, v163, v253
	ds_write_b32 v213, v163 offset:11264
	s_waitcnt vmcnt(23)
	v_mul_f32_e32 v253, 0xbfb8aa3b, v164
	v_exp_f32_e32 v253, v253
	s_nop 0
	v_add_f32_e32 v253, 1.0, v253
	v_rcp_f32_e32 v253, v253
	s_nop 0
	v_mul_f32_e32 v164, v164, v253
	ds_write_b32 v213, v164 offset:12288
	s_waitcnt vmcnt(22)
	v_mul_f32_e32 v253, 0xbfb8aa3b, v165
	v_exp_f32_e32 v253, v253
	s_nop 0
	v_add_f32_e32 v253, 1.0, v253
	v_rcp_f32_e32 v253, v253
	s_nop 0
	v_mul_f32_e32 v165, v165, v253
	ds_write_b32 v213, v165 offset:13312
	s_waitcnt vmcnt(21)
	v_mul_f32_e32 v253, 0xbfb8aa3b, v166
	v_exp_f32_e32 v253, v253
	s_nop 0
	v_add_f32_e32 v253, 1.0, v253
	v_rcp_f32_e32 v253, v253
	s_nop 0
	v_mul_f32_e32 v166, v166, v253
	ds_write_b32 v213, v166 offset:14336
	s_waitcnt vmcnt(20)
	v_mul_f32_e32 v253, 0xbfb8aa3b, v167
	v_exp_f32_e32 v253, v253
	s_nop 0
	v_add_f32_e32 v253, 1.0, v253
	v_rcp_f32_e32 v253, v253
	s_nop 0
	v_mul_f32_e32 v167, v167, v253
	ds_write_b32 v213, v167 offset:15360
	s_waitcnt vmcnt(19)
	v_mul_f32_e32 v253, 0xbfb8aa3b, v168
	v_exp_f32_e32 v253, v253
	s_nop 0
	v_add_f32_e32 v253, 1.0, v253
	v_rcp_f32_e32 v253, v253
	s_nop 0
	v_mul_f32_e32 v168, v168, v253
	ds_write_b32 v213, v168 offset:16384
	s_waitcnt vmcnt(18)
	v_mul_f32_e32 v253, 0xbfb8aa3b, v169
	v_exp_f32_e32 v253, v253
	s_nop 0
	v_add_f32_e32 v253, 1.0, v253
	v_rcp_f32_e32 v253, v253
	s_nop 0
	v_mul_f32_e32 v169, v169, v253
	ds_write_b32 v213, v169 offset:17408
	s_waitcnt vmcnt(17)
	v_mul_f32_e32 v253, 0xbfb8aa3b, v170
	v_exp_f32_e32 v253, v253
	s_nop 0
	v_add_f32_e32 v253, 1.0, v253
	v_rcp_f32_e32 v253, v253
	s_nop 0
	v_mul_f32_e32 v170, v170, v253
	ds_write_b32 v213, v170 offset:18432
	s_waitcnt vmcnt(16)
	v_mul_f32_e32 v253, 0xbfb8aa3b, v171
	v_exp_f32_e32 v253, v253
	s_nop 0
	v_add_f32_e32 v253, 1.0, v253
	v_rcp_f32_e32 v253, v253
	s_nop 0
	v_mul_f32_e32 v171, v171, v253
	ds_write_b32 v213, v171 offset:19456
	s_waitcnt vmcnt(15)
	v_mul_f32_e32 v253, 0xbfb8aa3b, v233
	v_exp_f32_e32 v253, v253
	s_nop 0
	v_add_f32_e32 v253, 1.0, v253
	v_rcp_f32_e32 v253, v253
	s_nop 0
	v_mul_f32_e32 v233, v233, v253
	ds_write_b32 v213, v233 offset:20480
	s_waitcnt vmcnt(14)
	v_mul_f32_e32 v253, 0xbfb8aa3b, v234
	v_exp_f32_e32 v253, v253
	s_nop 0
	v_add_f32_e32 v253, 1.0, v253
	v_rcp_f32_e32 v253, v253
	s_nop 0
	v_mul_f32_e32 v234, v234, v253
	ds_write_b32 v213, v234 offset:21504
	s_waitcnt vmcnt(13)
	v_mul_f32_e32 v253, 0xbfb8aa3b, v235
	v_exp_f32_e32 v253, v253
	s_nop 0
	v_add_f32_e32 v253, 1.0, v253
	v_rcp_f32_e32 v253, v253
	s_nop 0
	v_mul_f32_e32 v235, v235, v253
	ds_write_b32 v213, v235 offset:22528
	s_waitcnt vmcnt(12)
	v_mul_f32_e32 v253, 0xbfb8aa3b, v236
	v_exp_f32_e32 v253, v253
	s_nop 0
	v_add_f32_e32 v253, 1.0, v253
	v_rcp_f32_e32 v253, v253
	s_nop 0
	v_mul_f32_e32 v236, v236, v253
	ds_write_b32 v213, v236 offset:23552
	s_waitcnt vmcnt(11)
	v_mul_f32_e32 v253, 0xbfb8aa3b, v237
	v_exp_f32_e32 v253, v253
	s_nop 0
	v_add_f32_e32 v253, 1.0, v253
	v_rcp_f32_e32 v253, v253
	s_nop 0
	v_mul_f32_e32 v237, v237, v253
	ds_write_b32 v213, v237 offset:24576
	s_waitcnt vmcnt(10)
	v_mul_f32_e32 v253, 0xbfb8aa3b, v238
	v_exp_f32_e32 v253, v253
	s_nop 0
	v_add_f32_e32 v253, 1.0, v253
	v_rcp_f32_e32 v253, v253
	s_nop 0
	v_mul_f32_e32 v238, v238, v253
	ds_write_b32 v213, v238 offset:25600
	s_waitcnt vmcnt(9)
	v_mul_f32_e32 v253, 0xbfb8aa3b, v239
	v_exp_f32_e32 v253, v253
	s_nop 0
	v_add_f32_e32 v253, 1.0, v253
	v_rcp_f32_e32 v253, v253
	s_nop 0
	v_mul_f32_e32 v239, v239, v253
	ds_write_b32 v213, v239 offset:26624
	s_waitcnt vmcnt(8)
	v_mul_f32_e32 v253, 0xbfb8aa3b, v240
	v_exp_f32_e32 v253, v253
	s_nop 0
	v_add_f32_e32 v253, 1.0, v253
	v_rcp_f32_e32 v253, v253
	s_nop 0
	v_mul_f32_e32 v240, v240, v253
	ds_write_b32 v213, v240 offset:27648
	s_waitcnt vmcnt(7)
	v_mul_f32_e32 v253, 0xbfb8aa3b, v241
	v_exp_f32_e32 v253, v253
	s_nop 0
	v_add_f32_e32 v253, 1.0, v253
	v_rcp_f32_e32 v253, v253
	s_nop 0
	v_mul_f32_e32 v241, v241, v253
	ds_write_b32 v213, v241 offset:28672
	s_waitcnt vmcnt(6)
	v_mul_f32_e32 v253, 0xbfb8aa3b, v242
	v_exp_f32_e32 v253, v253
	s_nop 0
	v_add_f32_e32 v253, 1.0, v253
	v_rcp_f32_e32 v253, v253
	s_nop 0
	v_mul_f32_e32 v242, v242, v253
	ds_write_b32 v213, v242 offset:29696
	s_waitcnt vmcnt(5)
	v_mul_f32_e32 v253, 0xbfb8aa3b, v243
	v_exp_f32_e32 v253, v253
	s_nop 0
	v_add_f32_e32 v253, 1.0, v253
	v_rcp_f32_e32 v253, v253
	s_nop 0
	v_mul_f32_e32 v243, v243, v253
	ds_write_b32 v213, v243 offset:30720
	s_waitcnt vmcnt(4)
	v_mul_f32_e32 v253, 0xbfb8aa3b, v244
	v_exp_f32_e32 v253, v253
	s_nop 0
	v_add_f32_e32 v253, 1.0, v253
	v_rcp_f32_e32 v253, v253
	s_nop 0
	v_mul_f32_e32 v244, v244, v253
	ds_write_b32 v213, v244 offset:31744
	s_waitcnt vmcnt(3)
	v_mul_f32_e32 v253, 0xbfb8aa3b, v249
	v_exp_f32_e32 v253, v253
	s_nop 0
	v_add_f32_e32 v253, 1.0, v253
	v_rcp_f32_e32 v253, v253
	s_nop 0
	v_mul_f32_e32 v249, v249, v253
	ds_write_b32 v213, v249 offset:32768
	s_waitcnt vmcnt(2)
	v_mul_f32_e32 v253, 0xbfb8aa3b, v250
	v_exp_f32_e32 v253, v253
	s_nop 0
	v_add_f32_e32 v253, 1.0, v253
	v_rcp_f32_e32 v253, v253
	s_nop 0
	v_mul_f32_e32 v250, v250, v253
	ds_write_b32 v213, v250 offset:33792
	s_waitcnt vmcnt(1)
	v_mul_f32_e32 v253, 0xbfb8aa3b, v251
	v_exp_f32_e32 v253, v253
	s_nop 0
	v_add_f32_e32 v253, 1.0, v253
	v_rcp_f32_e32 v253, v253
	s_nop 0
	v_mul_f32_e32 v251, v251, v253
	ds_write_b32 v213, v251 offset:34816
	s_waitcnt vmcnt(0)
	v_mul_f32_e32 v253, 0xbfb8aa3b, v252
	v_exp_f32_e32 v253, v253
	s_nop 0
	v_add_f32_e32 v253, 1.0, v253
	v_rcp_f32_e32 v253, v253
	s_nop 0
	v_mul_f32_e32 v252, v252, v253
	ds_write_b32 v213, v252 offset:35840
	s_or_b64 exec, exec, s[0:1]
	s_mul_hi_i32 s0, s48, 0x2aaaaaab
	s_lshr_b32 s1, s0, 31
	s_ashr_i32 s2, s0, 4
	s_add_i32 s2, s2, s1
	s_mul_i32 s0, s2, 0x60
	s_sub_i32 s0, s48, s0
	s_lshl_b32 s0, s0, 5
	s_ashr_i32 s1, s0, 31
	s_mul_i32 s13, s2, 0xc00000
	s_lshl_b64 s[10:11], s[0:1], 2
	s_mul_hi_i32 s12, s2, 0xc00000
	s_add_u32 s10, s13, s10
	s_addc_u32 s11, s12, s11
	v_mov_b32_e32 v1, 0
	v_lshl_add_u64 v[74:75], v[146:147], 0, s[10:11]
	s_mov_b64 s[10:11], 0
	v_mov_b32_e32 v86, v214
	v_mov_b32_e32 v76, 0
	v_mov_b32_e32 v77, v1
	v_mov_b32_e32 v78, 0
	v_mov_b32_e32 v79, v1
	v_mov_b32_e32 v80, 0
	v_mov_b32_e32 v81, v1
	v_mov_b32_e32 v82, 0
	v_mov_b32_e32 v83, v1
	s_waitcnt lgkmcnt(0)
	s_barrier
